# attention loops: rescale factor exp2(m_old-m_new) computed only on the rare path where the row reference moves (1.0 otherwise): one transcendental less per tile
# baseline (speedup 1.0000x reference)
; __device__ __forceinline__ float max_x32(float v) { const unsigned u = __float_as_uint(v); auto r = __builtin_amdgcn_permlane32_swap(u, u, false, false); return fmaxf(__uint_as_float(r[0]), __uint_as_float(r[1])); }
; template <bool MASKED>
; __device__ __forceinline__ void softmax_tile(f32x16& s0, f32x16& s1, float& m, float& l, float& alpha, unsigned mlo, unsigned mhi, bf16x8 (&pk)[4]) {
;     ...
;     float mx = fmaxf(s0[0], s1[0]);
; #pragma unroll
;     for (int r = 1; r < 16; ++r) mx = fmaxf(mx, fmaxf(s0[r], s1[r]));
;     mx = max_x32(mx);
;     const float mn = fmaxf(m, mx);
;     alpha = __builtin_amdgcn_exp2f(m - mn); m = mn;
.LBB0_626:
	s_cmp_gt_i32 s7, s25
	s_cbranch_scc1 .LBB0_630
	s_mul_i32 s26, s17, 0xa000
	s_add_i32 s26, s26, 0
	v_add_u32_e32 v0, s26, v124
	v_add_u32_e32 v70, v0, v126
	v_add_u32_e32 v74, v0, v127
	ds_read_b128 v[66:69], v70
	ds_read_b128 v[70:73], v70 offset:8192
	ds_read_b128 v[150:153], v74
	ds_read_b128 v[154:157], v74 offset:8192
	v_add_u32_e32 v74, v0, v128
	v_add_u32_e32 v0, v0, v129
	ds_read_b128 v[158:161], v74
	ds_read_b128 v[162:165], v74 offset:8192
	ds_read_b128 v[166:169], v0
	ds_read_b128 v[170:173], v0 offset:8192
	s_waitcnt lgkmcnt(0)
	v_mfma_f32_32x32x16_bf16 v[82:97], v[66:69], v[98:101], v[236:251]
	v_mfma_f32_32x32x16_bf16 v[66:81], v[70:73], v[98:101], v[236:251]
	v_mfma_f32_32x32x16_bf16 v[82:97], v[150:153], v[102:105], v[82:97]
	v_mfma_f32_32x32x16_bf16 v[66:81], v[154:157], v[102:105], v[66:81]
	v_mfma_f32_32x32x16_bf16 v[82:97], v[158:161], v[106:109], v[82:97]
	v_mfma_f32_32x32x16_bf16 v[66:81], v[162:165], v[106:109], v[66:81]
	v_mfma_f32_32x32x16_bf16 v[82:97], v[166:169], v[110:113], v[82:97]
	v_mfma_f32_32x32x16_bf16 v[66:81], v[170:173], v[110:113], v[66:81]
	s_nop 11
	v_max3_f32 v150, v82, v83, v84
	v_max3_f32 v151, v85, v86, v87
	v_max3_f32 v152, v88, v89, v90
	v_max3_f32 v153, v91, v92, v93
	v_max3_f32 v154, v94, v95, v96
	v_max3_f32 v155, v97, v66, v67
	v_max3_f32 v156, v68, v69, v70
	v_max3_f32 v157, v71, v72, v73
	v_max3_f32 v158, v74, v75, v76
	v_max3_f32 v159, v77, v78, v79
	v_max3_f32 v150, v150, v151, v152
	v_max3_f32 v153, v153, v154, v155
	v_max3_f32 v156, v156, v157, v158
	v_max3_f32 v159, v159, v80, v81
	v_max3_f32 v150, v150, v153, v156
	v_max_f32_e32 v150, v150, v159
	v_mov_b32_e32 v151, v150
	s_nop 1
	v_permlane32_swap_b32_e32 v150, v151
	v_max_f32_e32 v146, v150, v151
	v_add_f32_e32 v146, v146, v252
	v_max_f32_e32 v146, v148, v146
	v_sub_f32_e32 v150, v146, v148
	v_cmp_lt_f32_e32 vcc, 8.0, v150
	s_nop 1
	v_cndmask_b32_e32 v146, v148, v146, vcc
	v_mov_b32_e32 v0, 1.0
	v_sub_f32_e32 v150, v146, v252
	v_cmp_neq_f32_e32 vcc, 0, v150
	s_cbranch_vccz .Lm2_cfast
	v_sub_f32_e32 v0, v148, v146
	v_exp_f32_e32 v0, v0
	v_sub_f32_e32 v82, v82, v150
	v_sub_f32_e32 v83, v83, v150
	v_sub_f32_e32 v84, v84, v150
	v_sub_f32_e32 v85, v85, v150
	v_sub_f32_e32 v86, v86, v150
	v_sub_f32_e32 v87, v87, v150
	v_sub_f32_e32 v88, v88, v150
	v_sub_f32_e32 v89, v89, v150
	v_sub_f32_e32 v90, v90, v150
	v_sub_f32_e32 v91, v91, v150
	v_sub_f32_e32 v92, v92, v150
	v_sub_f32_e32 v93, v93, v150
	v_sub_f32_e32 v94, v94, v150
	v_sub_f32_e32 v95, v95, v150
	v_sub_f32_e32 v96, v96, v150
	v_sub_f32_e32 v97, v97, v150
	v_sub_f32_e32 v66, v66, v150
	v_sub_f32_e32 v67, v67, v150
	v_sub_f32_e32 v68, v68, v150
	v_sub_f32_e32 v69, v69, v150
	v_sub_f32_e32 v70, v70, v150
	v_sub_f32_e32 v71, v71, v150
	v_sub_f32_e32 v72, v72, v150
	v_sub_f32_e32 v73, v73, v150
	v_sub_f32_e32 v74, v74, v150
	v_sub_f32_e32 v75, v75, v150
	v_sub_f32_e32 v76, v76, v150
	v_sub_f32_e32 v77, v77, v150
	v_sub_f32_e32 v78, v78, v150
	v_sub_f32_e32 v79, v79, v150
	v_sub_f32_e32 v80, v80, v150
	v_sub_f32_e32 v81, v81, v150
	v_mov_b32_e32 v252, v146
	v_sub_f32_e32 v236, 0, v146
	v_sub_f32_e32 v237, 0, v146
	v_sub_f32_e32 v238, 0, v146
	v_sub_f32_e32 v239, 0, v146
	v_sub_f32_e32 v240, 0, v146
	v_sub_f32_e32 v241, 0, v146
	v_sub_f32_e32 v242, 0, v146
	v_sub_f32_e32 v243, 0, v146
	v_sub_f32_e32 v244, 0, v146
	v_sub_f32_e32 v245, 0, v146
	v_sub_f32_e32 v246, 0, v146
	v_sub_f32_e32 v247, 0, v146
	v_sub_f32_e32 v248, 0, v146
	v_sub_f32_e32 v249, 0, v146
	v_sub_f32_e32 v250, 0, v146
	v_sub_f32_e32 v251, 0, v146
; __device__ __forceinline__ unsigned cvtpk(float lo, float hi) { unsigned r; asm("v_cvt_pk_bf16_f32 %0, %1, %2" : "=v"(r) : "v"(lo), "v"(hi)); return r; }
; template <bool MASKED>
; __device__ __forceinline__ void softmax_tile(f32x16& s0, f32x16& s1, float& m, float& l, float& alpha, unsigned mlo, unsigned mhi, bf16x8 (&pk)[4]) {
;     ...
;     alpha = __builtin_amdgcn_exp2f(m - mn); m = mn;
;     float sum = 0.f;
; #pragma unroll
;     for (int r = 0; r < 16; ++r) {
;         float p0 = __builtin_amdgcn_exp2f(s0[r] - mn), p1 = __builtin_amdgcn_exp2f(s1[r] - mn);
;         if (MASKED) { if (s0[r] <= -1e29f) p0 = 0.f; if (s1[r] <= -1e29f) p1 = 0.f; }
;         s0[r] = p0; s1[r] = p1; sum += p0 + p1;
;     }
;     l = l * alpha + sum;
; #pragma unroll
;     for (int k2 = 0; k2 < 2; ++k2) {
;         u32x4 a, b;
;         a.x = cvtpk(s0[8 * k2 + 0], s0[8 * k2 + 1]); a.y = cvtpk(s0[8 * k2 + 2], s0[8 * k2 + 3]); a.z = cvtpk(s0[8 * k2 + 4], s0[8 * k2 + 5]); a.w = cvtpk(s0[8 * k2 + 6], s0[8 * k2 + 7]);
;         b.x = cvtpk(s1[8 * k2 + 0], s1[8 * k2 + 1]); b.y = cvtpk(s1[8 * k2 + 2], s1[8 * k2 + 3]); b.z = cvtpk(s1[8 * k2 + 4], s1[8 * k2 + 5]); b.w = cvtpk(s1[8 * k2 + 6], s1[8 * k2 + 7]);
;         pk[k2] = __builtin_bit_cast(bf16x8, a); pk[2 + k2] = __builtin_bit_cast(bf16x8, b);
;     }
.Lm2_cfast:
	v_exp_f32_e32 v82, v82
	v_exp_f32_e32 v83, v83
	v_exp_f32_e32 v84, v84
	v_exp_f32_e32 v85, v85
	v_exp_f32_e32 v86, v86
	v_exp_f32_e32 v87, v87
	v_exp_f32_e32 v88, v88
	v_exp_f32_e32 v89, v89
	v_exp_f32_e32 v90, v90
	v_exp_f32_e32 v91, v91
	v_exp_f32_e32 v92, v92
	v_exp_f32_e32 v93, v93
	v_exp_f32_e32 v94, v94
	v_exp_f32_e32 v95, v95
	v_exp_f32_e32 v96, v96
	v_exp_f32_e32 v97, v97
	v_exp_f32_e32 v66, v66
	v_exp_f32_e32 v67, v67
	v_exp_f32_e32 v68, v68
	v_exp_f32_e32 v69, v69
	v_exp_f32_e32 v70, v70
	v_exp_f32_e32 v71, v71
	v_exp_f32_e32 v72, v72
	v_exp_f32_e32 v73, v73
	v_exp_f32_e32 v74, v74
	v_exp_f32_e32 v75, v75
	v_exp_f32_e32 v76, v76
	v_exp_f32_e32 v77, v77
	v_exp_f32_e32 v78, v78
	v_exp_f32_e32 v79, v79
	v_exp_f32_e32 v80, v80
	v_exp_f32_e32 v81, v81
	v_pk_add_f32 v[150:151], v[82:83], v[84:85]
	v_pk_add_f32 v[152:153], v[86:87], v[88:89]
	v_pk_add_f32 v[154:155], v[90:91], v[92:93]
	v_pk_add_f32 v[156:157], v[94:95], v[96:97]
	v_pk_add_f32 v[158:159], v[66:67], v[68:69]
	v_pk_add_f32 v[160:161], v[70:71], v[72:73]
	v_pk_add_f32 v[162:163], v[74:75], v[76:77]
	v_pk_add_f32 v[164:165], v[78:79], v[80:81]
	v_pk_add_f32 v[150:151], v[150:151], v[152:153]
	v_pk_add_f32 v[154:155], v[154:155], v[156:157]
	v_pk_add_f32 v[158:159], v[158:159], v[160:161]
	v_pk_add_f32 v[162:163], v[162:163], v[164:165]
	v_pk_add_f32 v[150:151], v[150:151], v[154:155]
	v_pk_add_f32 v[158:159], v[158:159], v[162:163]
	v_pk_add_f32 v[150:151], v[150:151], v[158:159]
	v_add_f32_e32 v164, v150, v151
	v_cvt_pk_bf16_f32 v66, v66, v67
	v_cvt_pk_bf16_f32 v67, v68, v69
	v_cvt_pk_bf16_f32 v68, v70, v71
	v_cvt_pk_bf16_f32 v69, v72, v73
	v_cvt_pk_bf16_f32 v70, v74, v75
	v_cvt_pk_bf16_f32 v71, v76, v77
	v_cvt_pk_bf16_f32 v72, v78, v79
	v_cvt_pk_bf16_f32 v73, v80, v81
	v_cvt_pk_bf16_f32 v74, v82, v83
	v_cvt_pk_bf16_f32 v75, v84, v85
	v_cvt_pk_bf16_f32 v76, v86, v87
	v_cvt_pk_bf16_f32 v77, v88, v89
	v_cvt_pk_bf16_f32 v78, v90, v91
	v_cvt_pk_bf16_f32 v79, v92, v93
	v_cvt_pk_bf16_f32 v80, v94, v95
	v_cvt_pk_bf16_f32 v81, v96, v97
	v_fmac_f32_e32 v164, v147, v0
	v_cmp_neq_f32_e32 vcc, 1.0, v0
	s_cbranch_vccz .LBB0_629
	v_pk_mul_f32 v[64:65], v[64:65], v[0:1] op_sel_hi:[1,0]
	v_pk_mul_f32 v[62:63], v[62:63], v[0:1] op_sel_hi:[1,0]
	v_pk_mul_f32 v[60:61], v[60:61], v[0:1] op_sel_hi:[1,0]
	v_pk_mul_f32 v[58:59], v[58:59], v[0:1] op_sel_hi:[1,0]
	v_pk_mul_f32 v[56:57], v[56:57], v[0:1] op_sel_hi:[1,0]
	v_pk_mul_f32 v[54:55], v[54:55], v[0:1] op_sel_hi:[1,0]
	v_pk_mul_f32 v[52:53], v[52:53], v[0:1] op_sel_hi:[1,0]
	v_pk_mul_f32 v[50:51], v[50:51], v[0:1] op_sel_hi:[1,0]
	v_pk_mul_f32 v[48:49], v[48:49], v[0:1] op_sel_hi:[1,0]
	v_pk_mul_f32 v[46:47], v[46:47], v[0:1] op_sel_hi:[1,0]
	v_pk_mul_f32 v[44:45], v[44:45], v[0:1] op_sel_hi:[1,0]
	v_pk_mul_f32 v[42:43], v[42:43], v[0:1] op_sel_hi:[1,0]
	v_pk_mul_f32 v[40:41], v[40:41], v[0:1] op_sel_hi:[1,0]
	v_pk_mul_f32 v[38:39], v[38:39], v[0:1] op_sel_hi:[1,0]
	v_pk_mul_f32 v[36:37], v[36:37], v[0:1] op_sel_hi:[1,0]
	v_pk_mul_f32 v[34:35], v[34:35], v[0:1] op_sel_hi:[1,0]
	v_pk_mul_f32 v[32:33], v[32:33], v[0:1] op_sel_hi:[1,0]
	v_pk_mul_f32 v[30:31], v[30:31], v[0:1] op_sel_hi:[1,0]
	v_pk_mul_f32 v[28:29], v[28:29], v[0:1] op_sel_hi:[1,0]
	v_pk_mul_f32 v[26:27], v[26:27], v[0:1] op_sel_hi:[1,0]
	v_pk_mul_f32 v[24:25], v[24:25], v[0:1] op_sel_hi:[1,0]
	v_pk_mul_f32 v[22:23], v[22:23], v[0:1] op_sel_hi:[1,0]
	v_pk_mul_f32 v[20:21], v[20:21], v[0:1] op_sel_hi:[1,0]
	v_pk_mul_f32 v[18:19], v[18:19], v[0:1] op_sel_hi:[1,0]
	v_pk_mul_f32 v[16:17], v[16:17], v[0:1] op_sel_hi:[1,0]
	v_pk_mul_f32 v[14:15], v[14:15], v[0:1] op_sel_hi:[1,0]
	v_pk_mul_f32 v[12:13], v[12:13], v[0:1] op_sel_hi:[1,0]
	v_pk_mul_f32 v[10:11], v[10:11], v[0:1] op_sel_hi:[1,0]
	v_pk_mul_f32 v[8:9], v[8:9], v[0:1] op_sel_hi:[1,0]
	v_pk_mul_f32 v[6:7], v[6:7], v[0:1] op_sel_hi:[1,0]
	v_pk_mul_f32 v[4:5], v[4:5], v[0:1] op_sel_hi:[1,0]
	v_pk_mul_f32 v[2:3], v[2:3], v[0:1] op_sel_hi:[1,0]

; __device__ __forceinline__ float max_x32(float v) { const unsigned u = __float_as_uint(v); auto r = __builtin_amdgcn_permlane32_swap(u, u, false, false); return fmaxf(__uint_as_float(r[0]), __uint_as_float(r[1])); }
; template <bool MASKED>
; __device__ __forceinline__ void softmax_tile(f32x16& s0, f32x16& s1, float& m, float& l, float& alpha, unsigned mlo, unsigned mhi, bf16x8 (&pk)[4]) {
;     ...
;         for (int r = 0; r < 16; ++r) { const int bit = (r & 3) + 8 * (r >> 2); if (!((mlo >> bit) & 1u)) s0[r] = NEG; if (!((mhi >> bit) & 1u)) s1[r] = NEG; }
;     }
;     float mx = fmaxf(s0[0], s1[0]);
; #pragma unroll
;     for (int r = 1; r < 16; ++r) mx = fmaxf(mx, fmaxf(s0[r], s1[r]));
;     mx = max_x32(mx);
;     const float mn = fmaxf(m, mx);
;     alpha = __builtin_amdgcn_exp2f(m - mn); m = mn;
.LBB0_1176:
	s_andn2_b64 vcc, exec, s[12:13]
	s_cbranch_vccnz .LBB0_1180
	s_mul_i32 s12, s17, 0xa000
	s_add_i32 s12, s12, 0
	v_add_u32_e32 v194, s12, v141
	v_add_u32_e32 v70, v194, v143
	v_add_u32_e32 v74, v194, v144
	ds_read_b128 v[66:69], v70
	ds_read_b128 v[70:73], v70 offset:8192
	ds_read_b128 v[160:163], v74
	ds_read_b128 v[164:167], v74 offset:8192
	v_add_u32_e32 v74, v194, v145
	ds_read_b128 v[168:171], v74
	ds_read_b128 v[172:175], v74 offset:8192
	v_add_u32_e32 v74, v194, v146
	ds_read_b128 v[186:189], v74 offset:8192
	ds_read_b128 v[190:193], v74
	s_waitcnt lgkmcnt(0)
	v_mfma_f32_32x32x16_bf16 v[82:97], v[66:69], v[98:101], v[236:251]
	v_mfma_f32_32x32x16_bf16 v[66:81], v[70:73], v[98:101], v[236:251]
	v_mfma_f32_32x32x16_bf16 v[82:97], v[160:163], v[102:105], v[82:97]
	v_mfma_f32_32x32x16_bf16 v[66:81], v[164:167], v[102:105], v[66:81]
	v_mfma_f32_32x32x16_bf16 v[82:97], v[168:171], v[106:109], v[82:97]
	v_mfma_f32_32x32x16_bf16 v[66:81], v[172:175], v[106:109], v[66:81]
	v_mfma_f32_32x32x16_bf16 v[82:97], v[190:193], v[110:113], v[82:97]
	v_mfma_f32_32x32x16_bf16 v[66:81], v[186:189], v[110:113], v[66:81]
	v_add_u32_e32 v164, v194, v147
	v_add_u32_e32 v172, v194, v148
	v_add_u32_e32 v190, v194, v149
	v_add_u32_e32 v198, v194, v150
	ds_read_b128 v[160:163], v164
	ds_read_b128 v[164:167], v164 offset:8192
	ds_read_b128 v[168:171], v172
	ds_read_b128 v[172:175], v172 offset:8192
	ds_read_b128 v[186:189], v190
	ds_read_b128 v[190:193], v190 offset:8192
	ds_read_b128 v[194:197], v198 offset:8192
	ds_read_b128 v[206:209], v198
	s_waitcnt lgkmcnt(0)
	v_mfma_f32_32x32x16_bf16 v[82:97], v[160:163], v[114:117], v[82:97]
	v_mfma_f32_32x32x16_bf16 v[66:81], v[164:167], v[114:117], v[66:81]
	v_mfma_f32_32x32x16_bf16 v[82:97], v[168:171], v[118:121], v[82:97]
	v_mfma_f32_32x32x16_bf16 v[66:81], v[172:175], v[118:121], v[66:81]
	v_mfma_f32_32x32x16_bf16 v[82:97], v[186:189], v[122:125], v[82:97]
	v_mfma_f32_32x32x16_bf16 v[66:81], v[190:193], v[122:125], v[66:81]
	v_mfma_f32_32x32x16_bf16 v[82:97], v[206:209], v[126:129], v[82:97]
	v_mfma_f32_32x32x16_bf16 v[66:81], v[194:197], v[126:129], v[66:81]
	v_bfe_i32 v160, v185, 0, 1
	v_bfe_i32 v161, v185, 1, 1
	v_bfe_i32 v162, v185, 2, 1
	v_bfe_i32 v163, v185, 3, 1
	v_bfe_i32 v164, v185, 8, 1
	v_bfe_i32 v165, v185, 9, 1
	v_bfe_i32 v166, v185, 10, 1
	v_bfe_i32 v167, v185, 11, 1
	v_bfe_i32 v168, v185, 16, 1
	v_bfe_i32 v169, v185, 17, 1
	v_bfe_i32 v170, v185, 18, 1
	v_bfe_i32 v171, v185, 19, 1
	v_bfe_i32 v172, v185, 24, 1
	v_bfe_i32 v173, v185, 25, 1
	v_bfe_i32 v174, v185, 26, 1
	v_bfe_i32 v175, v185, 27, 1
	v_bfe_i32 v186, v0, 0, 1
	v_bfe_i32 v187, v0, 1, 1
	v_bfe_i32 v188, v0, 2, 1
	v_bfe_i32 v189, v0, 3, 1
	v_bfe_i32 v190, v0, 8, 1
	v_bfe_i32 v191, v0, 9, 1
	v_bfe_i32 v192, v0, 10, 1
	v_bfe_i32 v193, v0, 11, 1
	v_bfe_i32 v194, v0, 16, 1
	v_bfe_i32 v195, v0, 17, 1
	v_bfe_i32 v196, v0, 18, 1
	v_bfe_i32 v197, v0, 19, 1
	v_bfe_i32 v198, v0, 24, 1
	v_bfe_i32 v199, v0, 25, 1
	v_bfe_i32 v206, v0, 26, 1
	v_bfe_i32 v207, v0, 27, 1
	v_bfi_b32 v82, v160, v82, v215
	v_bfi_b32 v83, v161, v83, v215
	v_bfi_b32 v84, v162, v84, v215
	v_bfi_b32 v85, v163, v85, v215
	v_bfi_b32 v86, v164, v86, v215
	v_bfi_b32 v87, v165, v87, v215
	v_bfi_b32 v88, v166, v88, v215
	v_bfi_b32 v89, v167, v89, v215
	v_bfi_b32 v90, v168, v90, v215
	v_bfi_b32 v91, v169, v91, v215
	v_bfi_b32 v92, v170, v92, v215
	v_bfi_b32 v93, v171, v93, v215
	v_bfi_b32 v94, v172, v94, v215
	v_bfi_b32 v95, v173, v95, v215
	v_bfi_b32 v96, v174, v96, v215
	v_bfi_b32 v97, v175, v97, v215
	v_bfi_b32 v66, v186, v66, v215
	v_bfi_b32 v67, v187, v67, v215
	v_bfi_b32 v68, v188, v68, v215
	v_bfi_b32 v69, v189, v69, v215
	v_bfi_b32 v70, v190, v70, v215
	v_bfi_b32 v71, v191, v71, v215
	v_bfi_b32 v72, v192, v72, v215
	v_bfi_b32 v73, v193, v73, v215
	v_bfi_b32 v74, v194, v74, v215
	v_bfi_b32 v75, v195, v75, v215
	v_bfi_b32 v76, v196, v76, v215
	v_bfi_b32 v77, v197, v77, v215
	v_bfi_b32 v78, v198, v78, v215
	v_bfi_b32 v79, v199, v79, v215
	v_bfi_b32 v80, v206, v80, v215
	v_bfi_b32 v81, v207, v81, v215
	v_max3_f32 v160, v82, v83, v84
	v_max3_f32 v161, v85, v86, v87
	v_max3_f32 v162, v88, v89, v90
	v_max3_f32 v163, v91, v92, v93
	v_max3_f32 v164, v94, v95, v96
	v_max3_f32 v165, v97, v66, v67
	v_max3_f32 v166, v68, v69, v70
	v_max3_f32 v167, v71, v72, v73
	v_max3_f32 v168, v74, v75, v76
	v_max3_f32 v169, v77, v78, v79
	v_max3_f32 v160, v160, v161, v162
	v_max3_f32 v163, v163, v164, v165
	v_max3_f32 v166, v166, v167, v168
	v_max3_f32 v169, v169, v80, v81
	v_max3_f32 v160, v160, v163, v166
	v_max_f32_e32 v160, v160, v169
	v_mov_b32_e32 v161, v160
	s_nop 1
	v_permlane32_swap_b32_e32 v160, v161
	v_max_f32_e32 v162, v160, v161
	v_add_f32_e32 v162, v162, v252
	v_max3_f32 v162, v184, v162, s97
	v_sub_f32_e32 v163, v162, v184
	v_cmp_lt_f32_e32 vcc, 8.0, v163
	s_nop 1
	v_cndmask_b32_e32 v162, v184, v162, vcc
	v_mov_b32_e32 v0, 1.0
	v_sub_f32_e32 v163, v162, v252
	v_cmp_lt_f32_e32 vcc, s97, v162
	s_nop 1
	v_cndmask_b32_e32 v163, 0, v163, vcc
	v_cndmask_b32_e32 v253, v252, v162, vcc
	v_cmp_neq_f32_e32 vcc, 0, v163
	s_cbranch_vccz .Lm1_cfast
	v_sub_f32_e32 v0, v184, v162
	v_exp_f32_e32 v0, v0
	v_sub_f32_e32 v82, v82, v163
	v_sub_f32_e32 v83, v83, v163
	v_sub_f32_e32 v84, v84, v163
	v_sub_f32_e32 v85, v85, v163
	v_sub_f32_e32 v86, v86, v163
	v_sub_f32_e32 v87, v87, v163
	v_sub_f32_e32 v88, v88, v163
	v_sub_f32_e32 v89, v89, v163
	v_sub_f32_e32 v90, v90, v163
	v_sub_f32_e32 v91, v91, v163
	v_sub_f32_e32 v92, v92, v163
	v_sub_f32_e32 v93, v93, v163
	v_sub_f32_e32 v94, v94, v163
	v_sub_f32_e32 v95, v95, v163
	v_sub_f32_e32 v96, v96, v163
	v_sub_f32_e32 v97, v97, v163
	v_sub_f32_e32 v66, v66, v163
	v_sub_f32_e32 v67, v67, v163
	v_sub_f32_e32 v68, v68, v163
	v_sub_f32_e32 v69, v69, v163
	v_sub_f32_e32 v70, v70, v163
	v_sub_f32_e32 v71, v71, v163
	v_sub_f32_e32 v72, v72, v163
	v_sub_f32_e32 v73, v73, v163
	v_sub_f32_e32 v74, v74, v163
	v_sub_f32_e32 v75, v75, v163
	v_sub_f32_e32 v76, v76, v163
	v_sub_f32_e32 v77, v77, v163
	v_sub_f32_e32 v78, v78, v163
	v_sub_f32_e32 v79, v79, v163
	v_sub_f32_e32 v80, v80, v163
	v_sub_f32_e32 v81, v81, v163
	v_mov_b32_e32 v252, v253
	v_sub_f32_e32 v236, 0, v253
	v_sub_f32_e32 v237, 0, v253
	v_sub_f32_e32 v238, 0, v253
	v_sub_f32_e32 v239, 0, v253
	v_sub_f32_e32 v240, 0, v253
	v_sub_f32_e32 v241, 0, v253
	v_sub_f32_e32 v242, 0, v253
	v_sub_f32_e32 v243, 0, v253
	v_sub_f32_e32 v244, 0, v253
	v_sub_f32_e32 v245, 0, v253
	v_sub_f32_e32 v246, 0, v253
	v_sub_f32_e32 v247, 0, v253
	v_sub_f32_e32 v248, 0, v253
	v_sub_f32_e32 v249, 0, v253
	v_sub_f32_e32 v250, 0, v253
	v_sub_f32_e32 v251, 0, v253
; __device__ __forceinline__ unsigned cvtpk(float lo, float hi) { unsigned r; asm("v_cvt_pk_bf16_f32 %0, %1, %2" : "=v"(r) : "v"(lo), "v"(hi)); return r; }
; template <bool MASKED>
; __device__ __forceinline__ void softmax_tile(f32x16& s0, f32x16& s1, float& m, float& l, float& alpha, unsigned mlo, unsigned mhi, bf16x8 (&pk)[4]) {
;     ...
;     alpha = __builtin_amdgcn_exp2f(m - mn); m = mn;
;     float sum = 0.f;
; #pragma unroll
;     for (int r = 0; r < 16; ++r) {
;         float p0 = __builtin_amdgcn_exp2f(s0[r] - mn), p1 = __builtin_amdgcn_exp2f(s1[r] - mn);
;         if (MASKED) { if (s0[r] <= -1e29f) p0 = 0.f; if (s1[r] <= -1e29f) p1 = 0.f; }
;         s0[r] = p0; s1[r] = p1; sum += p0 + p1;
;     }
;     l = l * alpha + sum;
; #pragma unroll
;     for (int k2 = 0; k2 < 2; ++k2) {
;         u32x4 a, b;
;         a.x = cvtpk(s0[8 * k2 + 0], s0[8 * k2 + 1]); a.y = cvtpk(s0[8 * k2 + 2], s0[8 * k2 + 3]); a.z = cvtpk(s0[8 * k2 + 4], s0[8 * k2 + 5]); a.w = cvtpk(s0[8 * k2 + 6], s0[8 * k2 + 7]);
;         b.x = cvtpk(s1[8 * k2 + 0], s1[8 * k2 + 1]); b.y = cvtpk(s1[8 * k2 + 2], s1[8 * k2 + 3]); b.z = cvtpk(s1[8 * k2 + 4], s1[8 * k2 + 5]); b.w = cvtpk(s1[8 * k2 + 6], s1[8 * k2 + 7]);
;         pk[k2] = __builtin_bit_cast(bf16x8, a); pk[2 + k2] = __builtin_bit_cast(bf16x8, b);
;     }
.Lm1_cfast:
	v_exp_f32_e32 v82, v82
	v_exp_f32_e32 v83, v83
	v_exp_f32_e32 v84, v84
	v_exp_f32_e32 v85, v85
	v_exp_f32_e32 v86, v86
	v_exp_f32_e32 v87, v87
	v_exp_f32_e32 v88, v88
	v_exp_f32_e32 v89, v89
	v_exp_f32_e32 v90, v90
	v_exp_f32_e32 v91, v91
	v_exp_f32_e32 v92, v92
	v_exp_f32_e32 v93, v93
	v_exp_f32_e32 v94, v94
	v_exp_f32_e32 v95, v95
	v_exp_f32_e32 v96, v96
	v_exp_f32_e32 v97, v97
	v_exp_f32_e32 v66, v66
	v_exp_f32_e32 v67, v67
	v_exp_f32_e32 v68, v68
	v_exp_f32_e32 v69, v69
	v_exp_f32_e32 v70, v70
	v_exp_f32_e32 v71, v71
	v_exp_f32_e32 v72, v72
	v_exp_f32_e32 v73, v73
	v_exp_f32_e32 v74, v74
	v_exp_f32_e32 v75, v75
	v_exp_f32_e32 v76, v76
	v_exp_f32_e32 v77, v77
	v_exp_f32_e32 v78, v78
	v_exp_f32_e32 v79, v79
	v_exp_f32_e32 v80, v80
	v_exp_f32_e32 v81, v81
	v_pk_add_f32 v[164:165], v[82:83], v[84:85]
	v_pk_add_f32 v[166:167], v[86:87], v[88:89]
	v_pk_add_f32 v[168:169], v[90:91], v[92:93]
	v_pk_add_f32 v[170:171], v[94:95], v[96:97]
	v_pk_add_f32 v[172:173], v[66:67], v[68:69]
	v_pk_add_f32 v[174:175], v[70:71], v[72:73]
	v_pk_add_f32 v[186:187], v[74:75], v[76:77]
	v_pk_add_f32 v[188:189], v[78:79], v[80:81]
	v_pk_add_f32 v[164:165], v[164:165], v[166:167]
	v_pk_add_f32 v[168:169], v[168:169], v[170:171]
	v_pk_add_f32 v[172:173], v[172:173], v[174:175]
	v_pk_add_f32 v[186:187], v[186:187], v[188:189]
	v_pk_add_f32 v[164:165], v[164:165], v[168:169]
	v_pk_add_f32 v[172:173], v[172:173], v[186:187]
	v_pk_add_f32 v[164:165], v[164:165], v[172:173]
	v_add_f32_e32 v164, v164, v165
	v_cvt_pk_bf16_f32 v66, v66, v67
	v_cvt_pk_bf16_f32 v67, v68, v69
	v_cvt_pk_bf16_f32 v68, v70, v71
	v_cvt_pk_bf16_f32 v69, v72, v73
	v_cvt_pk_bf16_f32 v70, v74, v75
	v_cvt_pk_bf16_f32 v71, v76, v77
	v_cvt_pk_bf16_f32 v72, v78, v79
	v_cvt_pk_bf16_f32 v73, v80, v81
	v_cvt_pk_bf16_f32 v74, v82, v83
	v_cvt_pk_bf16_f32 v75, v84, v85
	v_cvt_pk_bf16_f32 v76, v86, v87
	v_cvt_pk_bf16_f32 v77, v88, v89
	v_cvt_pk_bf16_f32 v78, v90, v91
	v_cvt_pk_bf16_f32 v79, v92, v93
	v_cvt_pk_bf16_f32 v80, v94, v95
	v_cvt_pk_bf16_f32 v81, v96, v97
	v_fmac_f32_e32 v164, v183, v0
	v_mov_b32_e32 v83, v164
	v_mov_b32_e32 v82, v162
	v_cmp_neq_f32_e32 vcc, 1.0, v0
	s_cbranch_vccz .LBB0_1179
	v_pk_mul_f32 v[64:65], v[64:65], v[0:1] op_sel_hi:[1,0]
	v_pk_mul_f32 v[62:63], v[62:63], v[0:1] op_sel_hi:[1,0]
	v_pk_mul_f32 v[60:61], v[60:61], v[0:1] op_sel_hi:[1,0]
	v_pk_mul_f32 v[58:59], v[58:59], v[0:1] op_sel_hi:[1,0]
	v_pk_mul_f32 v[56:57], v[56:57], v[0:1] op_sel_hi:[1,0]
	v_pk_mul_f32 v[54:55], v[54:55], v[0:1] op_sel_hi:[1,0]
	v_pk_mul_f32 v[52:53], v[52:53], v[0:1] op_sel_hi:[1,0]
	v_pk_mul_f32 v[50:51], v[50:51], v[0:1] op_sel_hi:[1,0]
	v_pk_mul_f32 v[48:49], v[48:49], v[0:1] op_sel_hi:[1,0]
	v_pk_mul_f32 v[46:47], v[46:47], v[0:1] op_sel_hi:[1,0]
	v_pk_mul_f32 v[44:45], v[44:45], v[0:1] op_sel_hi:[1,0]
	v_pk_mul_f32 v[42:43], v[42:43], v[0:1] op_sel_hi:[1,0]
	v_pk_mul_f32 v[40:41], v[40:41], v[0:1] op_sel_hi:[1,0]
	v_pk_mul_f32 v[38:39], v[38:39], v[0:1] op_sel_hi:[1,0]
	v_pk_mul_f32 v[36:37], v[36:37], v[0:1] op_sel_hi:[1,0]
	v_pk_mul_f32 v[34:35], v[34:35], v[0:1] op_sel_hi:[1,0]
	v_pk_mul_f32 v[32:33], v[32:33], v[0:1] op_sel_hi:[1,0]
	v_pk_mul_f32 v[30:31], v[30:31], v[0:1] op_sel_hi:[1,0]
	v_pk_mul_f32 v[28:29], v[28:29], v[0:1] op_sel_hi:[1,0]
	v_pk_mul_f32 v[26:27], v[26:27], v[0:1] op_sel_hi:[1,0]
	v_pk_mul_f32 v[24:25], v[24:25], v[0:1] op_sel_hi:[1,0]
	v_pk_mul_f32 v[22:23], v[22:23], v[0:1] op_sel_hi:[1,0]
	v_pk_mul_f32 v[20:21], v[20:21], v[0:1] op_sel_hi:[1,0]
	v_pk_mul_f32 v[18:19], v[18:19], v[0:1] op_sel_hi:[1,0]
	v_pk_mul_f32 v[16:17], v[16:17], v[0:1] op_sel_hi:[1,0]
	v_pk_mul_f32 v[14:15], v[14:15], v[0:1] op_sel_hi:[1,0]
	v_pk_mul_f32 v[12:13], v[12:13], v[0:1] op_sel_hi:[1,0]
	v_pk_mul_f32 v[10:11], v[10:11], v[0:1] op_sel_hi:[1,0]
	v_pk_mul_f32 v[8:9], v[8:9], v[0:1] op_sel_hi:[1,0]
	v_pk_mul_f32 v[6:7], v[6:7], v[0:1] op_sel_hi:[1,0]
	v_pk_mul_f32 v[4:5], v[4:5], v[0:1] op_sel_hi:[1,0]
	v_pk_mul_f32 v[2:3], v[2:3], v[0:1] op_sel_hi:[1,0]

; __device__ __forceinline__ float max_x32(float v) { const unsigned u = __float_as_uint(v); auto r = __builtin_amdgcn_permlane32_swap(u, u, false, false); return fmaxf(__uint_as_float(r[0]), __uint_as_float(r[1])); }
; template <bool MASKED>
; __device__ __forceinline__ void softmax_tile(f32x16& s0, f32x16& s1, float& m, float& l, float& alpha, unsigned mlo, unsigned mhi, bf16x8 (&pk)[4]) {
;     ...
;     float mx = fmaxf(s0[0], s1[0]);
; #pragma unroll
;     for (int r = 1; r < 16; ++r) mx = fmaxf(mx, fmaxf(s0[r], s1[r]));
;     mx = max_x32(mx);
;     const float mn = fmaxf(m, mx);
;     alpha = __builtin_amdgcn_exp2f(m - mn); m = mn;
.LBB0_1190:
	s_cmp_gt_i32 s14, s49
	s_cbranch_scc1 .LBB0_1194
	s_mul_i32 s15, s50, 0xa000
	s_add_i32 s15, s15, 0
	v_add_u32_e32 v0, s15, v186
	v_add_u32_e32 v6, v0, v188
	v_add_u32_e32 v14, v0, v189
	ds_read_b128 v[2:5], v6
	ds_read_b128 v[6:9], v6 offset:8192
	ds_read_b128 v[10:13], v14
	ds_read_b128 v[160:163], v14 offset:8192
	v_add_u32_e32 v14, v0, v190
	ds_read_b128 v[164:167], v14
	ds_read_b128 v[168:171], v14 offset:8192
	v_add_u32_e32 v14, v0, v191
	ds_read_b128 v[172:175], v14 offset:8192
	ds_read_b128 v[206:209], v14
	v_add_u32_e32 v14, s15, v177
	s_waitcnt lgkmcnt(0)
	v_mfma_f32_32x32x16_bf16 v[96:111], v[2:5], v[112:115], v[236:251]
	v_mfma_f32_32x32x16_bf16 v[80:95], v[6:9], v[112:115], v[236:251]
	v_mfma_f32_32x32x16_bf16 v[96:111], v[10:13], v[116:119], v[96:111]
	v_mfma_f32_32x32x16_bf16 v[80:95], v[160:163], v[116:119], v[80:95]
	v_mfma_f32_32x32x16_bf16 v[96:111], v[164:167], v[120:123], v[96:111]
	v_mfma_f32_32x32x16_bf16 v[80:95], v[168:171], v[120:123], v[80:95]
	v_mfma_f32_32x32x16_bf16 v[96:111], v[206:209], v[124:127], v[96:111]
	v_mfma_f32_32x32x16_bf16 v[80:95], v[172:175], v[124:127], v[80:95]
	v_add_u32_e32 v6, v0, v192
	v_add_u32_e32 v15, v0, v193
	ds_read_b128 v[2:5], v6
	ds_read_b128 v[6:9], v6 offset:8192
	ds_read_b128 v[10:13], v15
	ds_read_b128 v[160:163], v15 offset:8192
	v_add_u32_e32 v15, v0, v194
	v_add_u32_e32 v0, v0, v195
	ds_read_b128 v[164:167], v15
	ds_read_b128 v[168:171], v15 offset:8192
	ds_read_b128 v[172:175], v0 offset:8192
	ds_read_b128 v[206:209], v0
	s_waitcnt lgkmcnt(0)
	v_mfma_f32_32x32x16_bf16 v[96:111], v[2:5], v[128:131], v[96:111]
	v_mfma_f32_32x32x16_bf16 v[80:95], v[6:9], v[128:131], v[80:95]
	v_mfma_f32_32x32x16_bf16 v[96:111], v[10:13], v[132:135], v[96:111]
	v_mfma_f32_32x32x16_bf16 v[80:95], v[160:163], v[132:135], v[80:95]
	v_mfma_f32_32x32x16_bf16 v[96:111], v[164:167], v[136:139], v[96:111]
	v_mfma_f32_32x32x16_bf16 v[80:95], v[168:171], v[136:139], v[80:95]
	v_mfma_f32_32x32x16_bf16 v[96:111], v[206:209], v[140:143], v[96:111]
	v_mfma_f32_32x32x16_bf16 v[80:95], v[172:175], v[140:143], v[80:95]
	v_add_u32_e32 v0, v14, v196
	ds_read_b128 v[2:5], v0 offset:32768
	ds_read_b128 v[6:9], v0 offset:36864
	v_add_u32_e32 v0, v14, v197
	ds_read_b128 v[10:13], v0 offset:32768
	ds_read_b128 v[160:163], v0 offset:36864
	v_add_u32_e32 v0, v14, v198
	ds_read_b128 v[164:167], v0 offset:32768
	ds_read_b128 v[168:171], v0 offset:36864
	v_add_u32_e32 v0, v14, v199
	ds_read_b128 v[172:175], v0 offset:36864
	ds_read_b128 v[206:209], v0 offset:32768
	s_waitcnt lgkmcnt(0)
	v_mfma_f32_32x32x16_bf16 v[96:111], v[2:5], v[144:147], v[96:111]
	v_mfma_f32_32x32x16_bf16 v[80:95], v[6:9], v[144:147], v[80:95]
	v_mfma_f32_32x32x16_bf16 v[96:111], v[10:13], v[148:151], v[96:111]
	v_mfma_f32_32x32x16_bf16 v[80:95], v[160:163], v[148:151], v[80:95]
	v_mfma_f32_32x32x16_bf16 v[96:111], v[164:167], v[152:155], v[96:111]
	v_mfma_f32_32x32x16_bf16 v[80:95], v[168:171], v[152:155], v[80:95]
	v_mfma_f32_32x32x16_bf16 v[96:111], v[206:209], v[156:159], v[96:111]
	v_mfma_f32_32x32x16_bf16 v[80:95], v[172:175], v[156:159], v[80:95]
	s_nop 11
	v_max3_f32 v160, v96, v97, v98
	v_max3_f32 v161, v99, v100, v101
	v_max3_f32 v162, v102, v103, v104
	v_max3_f32 v163, v105, v106, v107
	v_max3_f32 v164, v108, v109, v110
	v_max3_f32 v165, v111, v80, v81
	v_max3_f32 v166, v82, v83, v84
	v_max3_f32 v167, v85, v86, v87
	v_max3_f32 v168, v88, v89, v90
	v_max3_f32 v169, v91, v92, v93
	v_max3_f32 v160, v160, v161, v162
	v_max3_f32 v163, v163, v164, v165
	v_max3_f32 v166, v166, v167, v168
	v_max3_f32 v169, v169, v94, v95
	v_max3_f32 v160, v160, v163, v166
	v_max_f32_e32 v160, v160, v169
	v_mov_b32_e32 v161, v160
	s_nop 1
	v_permlane32_swap_b32_e32 v160, v161
	v_max_f32_e32 v14, v160, v161
	v_add_f32_e32 v14, v14, v252
	v_max_f32_e32 v14, v235, v14
	v_sub_f32_e32 v160, v14, v235
	v_cmp_lt_f32_e32 vcc, 8.0, v160
	s_nop 1
	v_cndmask_b32_e32 v14, v235, v14, vcc
	v_mov_b32_e32 v0, 1.0
	v_sub_f32_e32 v160, v14, v252
	v_cmp_neq_f32_e32 vcc, 0, v160
	s_cbranch_vccz .Lm0_cfast
	v_sub_f32_e32 v0, v235, v14
	v_exp_f32_e32 v0, v0
	v_sub_f32_e32 v96, v96, v160
	v_sub_f32_e32 v97, v97, v160
	v_sub_f32_e32 v98, v98, v160
	v_sub_f32_e32 v99, v99, v160
	v_sub_f32_e32 v100, v100, v160
	v_sub_f32_e32 v101, v101, v160
	v_sub_f32_e32 v102, v102, v160
	v_sub_f32_e32 v103, v103, v160
	v_sub_f32_e32 v104, v104, v160
	v_sub_f32_e32 v105, v105, v160
	v_sub_f32_e32 v106, v106, v160
	v_sub_f32_e32 v107, v107, v160
	v_sub_f32_e32 v108, v108, v160
	v_sub_f32_e32 v109, v109, v160
	v_sub_f32_e32 v110, v110, v160
	v_sub_f32_e32 v111, v111, v160
	v_sub_f32_e32 v80, v80, v160
	v_sub_f32_e32 v81, v81, v160
	v_sub_f32_e32 v82, v82, v160
	v_sub_f32_e32 v83, v83, v160
	v_sub_f32_e32 v84, v84, v160
	v_sub_f32_e32 v85, v85, v160
	v_sub_f32_e32 v86, v86, v160
	v_sub_f32_e32 v87, v87, v160
	v_sub_f32_e32 v88, v88, v160
	v_sub_f32_e32 v89, v89, v160
	v_sub_f32_e32 v90, v90, v160
	v_sub_f32_e32 v91, v91, v160
	v_sub_f32_e32 v92, v92, v160
	v_sub_f32_e32 v93, v93, v160
	v_sub_f32_e32 v94, v94, v160
	v_sub_f32_e32 v95, v95, v160
	v_mov_b32_e32 v252, v14
	v_sub_f32_e32 v236, 0, v14
	v_sub_f32_e32 v237, 0, v14
	v_sub_f32_e32 v238, 0, v14
	v_sub_f32_e32 v239, 0, v14
	v_sub_f32_e32 v240, 0, v14
	v_sub_f32_e32 v241, 0, v14
	v_sub_f32_e32 v242, 0, v14
	v_sub_f32_e32 v243, 0, v14
	v_sub_f32_e32 v244, 0, v14
	v_sub_f32_e32 v245, 0, v14
	v_sub_f32_e32 v246, 0, v14
	v_sub_f32_e32 v247, 0, v14
	v_sub_f32_e32 v248, 0, v14
	v_sub_f32_e32 v249, 0, v14
	v_sub_f32_e32 v250, 0, v14
	v_sub_f32_e32 v251, 0, v14
; __device__ __forceinline__ unsigned cvtpk(float lo, float hi) { unsigned r; asm("v_cvt_pk_bf16_f32 %0, %1, %2" : "=v"(r) : "v"(lo), "v"(hi)); return r; }
; template <bool MASKED>
; __device__ __forceinline__ void softmax_tile(f32x16& s0, f32x16& s1, float& m, float& l, float& alpha, unsigned mlo, unsigned mhi, bf16x8 (&pk)[4]) {
;     ...
;     alpha = __builtin_amdgcn_exp2f(m - mn); m = mn;
;     float sum = 0.f;
; #pragma unroll
;     for (int r = 0; r < 16; ++r) {
;         float p0 = __builtin_amdgcn_exp2f(s0[r] - mn), p1 = __builtin_amdgcn_exp2f(s1[r] - mn);
;         if (MASKED) { if (s0[r] <= -1e29f) p0 = 0.f; if (s1[r] <= -1e29f) p1 = 0.f; }
;         s0[r] = p0; s1[r] = p1; sum += p0 + p1;
;     }
;     l = l * alpha + sum;
; #pragma unroll
;     for (int k2 = 0; k2 < 2; ++k2) {
;         u32x4 a, b;
;         a.x = cvtpk(s0[8 * k2 + 0], s0[8 * k2 + 1]); a.y = cvtpk(s0[8 * k2 + 2], s0[8 * k2 + 3]); a.z = cvtpk(s0[8 * k2 + 4], s0[8 * k2 + 5]); a.w = cvtpk(s0[8 * k2 + 6], s0[8 * k2 + 7]);
;         b.x = cvtpk(s1[8 * k2 + 0], s1[8 * k2 + 1]); b.y = cvtpk(s1[8 * k2 + 2], s1[8 * k2 + 3]); b.z = cvtpk(s1[8 * k2 + 4], s1[8 * k2 + 5]); b.w = cvtpk(s1[8 * k2 + 6], s1[8 * k2 + 7]);
;         pk[k2] = __builtin_bit_cast(bf16x8, a); pk[2 + k2] = __builtin_bit_cast(bf16x8, b);
;     }
.Lm0_cfast:
	v_exp_f32_e32 v96, v96
	v_exp_f32_e32 v97, v97
	v_exp_f32_e32 v98, v98
	v_exp_f32_e32 v99, v99
	v_exp_f32_e32 v100, v100
	v_exp_f32_e32 v101, v101
	v_exp_f32_e32 v102, v102
	v_exp_f32_e32 v103, v103
	v_exp_f32_e32 v104, v104
	v_exp_f32_e32 v105, v105
	v_exp_f32_e32 v106, v106
	v_exp_f32_e32 v107, v107
	v_exp_f32_e32 v108, v108
	v_exp_f32_e32 v109, v109
	v_exp_f32_e32 v110, v110
	v_exp_f32_e32 v111, v111
	v_exp_f32_e32 v80, v80
	v_exp_f32_e32 v81, v81
	v_exp_f32_e32 v82, v82
	v_exp_f32_e32 v83, v83
	v_exp_f32_e32 v84, v84
	v_exp_f32_e32 v85, v85
	v_exp_f32_e32 v86, v86
	v_exp_f32_e32 v87, v87
	v_exp_f32_e32 v88, v88
	v_exp_f32_e32 v89, v89
	v_exp_f32_e32 v90, v90
	v_exp_f32_e32 v91, v91
	v_exp_f32_e32 v92, v92
	v_exp_f32_e32 v93, v93
	v_exp_f32_e32 v94, v94
	v_exp_f32_e32 v95, v95
	v_pk_add_f32 v[160:161], v[96:97], v[98:99]
	v_pk_add_f32 v[162:163], v[100:101], v[102:103]
	v_pk_add_f32 v[164:165], v[104:105], v[106:107]
	v_pk_add_f32 v[166:167], v[108:109], v[110:111]
	v_pk_add_f32 v[168:169], v[80:81], v[82:83]
	v_pk_add_f32 v[170:171], v[84:85], v[86:87]
	v_pk_add_f32 v[172:173], v[88:89], v[90:91]
	v_pk_add_f32 v[174:175], v[92:93], v[94:95]
	v_pk_add_f32 v[160:161], v[160:161], v[162:163]
	v_pk_add_f32 v[164:165], v[164:165], v[166:167]
	v_pk_add_f32 v[168:169], v[168:169], v[170:171]
	v_pk_add_f32 v[172:173], v[172:173], v[174:175]
	v_pk_add_f32 v[160:161], v[160:161], v[164:165]
	v_pk_add_f32 v[168:169], v[168:169], v[172:173]
	v_pk_add_f32 v[160:161], v[160:161], v[168:169]
	v_add_f32_e32 v15, v160, v161
	v_cvt_pk_bf16_f32 v2, v80, v81
	v_cvt_pk_bf16_f32 v3, v82, v83
	v_cvt_pk_bf16_f32 v4, v84, v85
	v_cvt_pk_bf16_f32 v5, v86, v87
	v_cvt_pk_bf16_f32 v6, v88, v89
	v_cvt_pk_bf16_f32 v7, v90, v91
	v_cvt_pk_bf16_f32 v8, v92, v93
	v_cvt_pk_bf16_f32 v9, v94, v95
	v_cvt_pk_bf16_f32 v80, v104, v105
	v_cvt_pk_bf16_f32 v81, v106, v107
	v_cvt_pk_bf16_f32 v82, v108, v109
	v_cvt_pk_bf16_f32 v83, v110, v111
	v_cvt_pk_bf16_f32 v10, v96, v97
	v_cvt_pk_bf16_f32 v11, v98, v99
	v_cvt_pk_bf16_f32 v12, v100, v101
	v_cvt_pk_bf16_f32 v13, v102, v103
	v_fmac_f32_e32 v15, v234, v0
	v_cmp_neq_f32_e32 vcc, 1.0, v0
	s_cbranch_vccz .LBB0_1193
	v_pk_mul_f32 v[78:79], v[78:79], v[0:1] op_sel_hi:[1,0]
	v_pk_mul_f32 v[76:77], v[76:77], v[0:1] op_sel_hi:[1,0]
	v_pk_mul_f32 v[74:75], v[74:75], v[0:1] op_sel_hi:[1,0]
	v_pk_mul_f32 v[72:73], v[72:73], v[0:1] op_sel_hi:[1,0]
	v_pk_mul_f32 v[70:71], v[70:71], v[0:1] op_sel_hi:[1,0]
	v_pk_mul_f32 v[68:69], v[68:69], v[0:1] op_sel_hi:[1,0]
	v_pk_mul_f32 v[66:67], v[66:67], v[0:1] op_sel_hi:[1,0]
	v_pk_mul_f32 v[64:65], v[64:65], v[0:1] op_sel_hi:[1,0]
	v_pk_mul_f32 v[62:63], v[62:63], v[0:1] op_sel_hi:[1,0]
	v_pk_mul_f32 v[60:61], v[60:61], v[0:1] op_sel_hi:[1,0]
	v_pk_mul_f32 v[58:59], v[58:59], v[0:1] op_sel_hi:[1,0]
	v_pk_mul_f32 v[56:57], v[56:57], v[0:1] op_sel_hi:[1,0]
	v_pk_mul_f32 v[54:55], v[54:55], v[0:1] op_sel_hi:[1,0]
	v_pk_mul_f32 v[52:53], v[52:53], v[0:1] op_sel_hi:[1,0]
	v_pk_mul_f32 v[50:51], v[50:51], v[0:1] op_sel_hi:[1,0]
	v_pk_mul_f32 v[48:49], v[48:49], v[0:1] op_sel_hi:[1,0]
	v_pk_mul_f32 v[46:47], v[46:47], v[0:1] op_sel_hi:[1,0]
	v_pk_mul_f32 v[44:45], v[44:45], v[0:1] op_sel_hi:[1,0]
	v_pk_mul_f32 v[42:43], v[42:43], v[0:1] op_sel_hi:[1,0]
	v_pk_mul_f32 v[40:41], v[40:41], v[0:1] op_sel_hi:[1,0]
	v_pk_mul_f32 v[38:39], v[38:39], v[0:1] op_sel_hi:[1,0]
	v_pk_mul_f32 v[36:37], v[36:37], v[0:1] op_sel_hi:[1,0]
	v_pk_mul_f32 v[34:35], v[34:35], v[0:1] op_sel_hi:[1,0]
	v_pk_mul_f32 v[32:33], v[32:33], v[0:1] op_sel_hi:[1,0]
	v_pk_mul_f32 v[30:31], v[30:31], v[0:1] op_sel_hi:[1,0]
	v_pk_mul_f32 v[28:29], v[28:29], v[0:1] op_sel_hi:[1,0]
	v_pk_mul_f32 v[26:27], v[26:27], v[0:1] op_sel_hi:[1,0]
	v_pk_mul_f32 v[24:25], v[24:25], v[0:1] op_sel_hi:[1,0]
	v_pk_mul_f32 v[22:23], v[22:23], v[0:1] op_sel_hi:[1,0]
	v_pk_mul_f32 v[20:21], v[20:21], v[0:1] op_sel_hi:[1,0]
	v_pk_mul_f32 v[18:19], v[18:19], v[0:1] op_sel_hi:[1,0]
	v_pk_mul_f32 v[16:17], v[16:17], v[0:1] op_sel_hi:[1,0]
